# s5_tables: the eight late C/B parameter loads preloaded at the top of the item into untouched VGPRs (late loads become moves), hiding 3-4 L2 round trips behind the transcendental math
# speedup vs baseline: 1.0027x; 1.0027x over previous
; DEV void s5_tables(LAS char* shm, char* tab, const float* lam_re, const float* lam_im, const float* log_dt, const float* b_re, const float* b_im,
;                    const float* c_re, const float* c_im) {
;     ...
;             const float lr = lam_re[g * NP + pp], li = lam_im[g * NP + pp], dt = expf(log_dt[g]);
;             const float xr = lr * dt, xi = li * dt;
; #pragma unroll
;             for (int k = 0; k < 5; ++k) {
;                 const int e = eg + 8 * k;
;                 if (e <= 32) {
;                     const float m_ = expf((float)e * xr); float sn, cs; sincosf((float)e * xi, &sn, &cs);
;     ...
;             for (int e = 0; e < 2; ++e) { const int o = tid + 512 * e, c = o >> 6, p2 = o & 63;
;                 cc[p2 * 16 + c] = (f32x2){c_re[(g * GC + c) * NP + p2], c_im[(g * GC + c) * NP + p2]}; }
;         }
;         __syncthreads();
;         for (int o = tid; o < 1024; o += 512) {
;             const int pp = o >> 4, c = o & 15; const f32x2 z = crv[pp];
;             const float br = b_re[(g * NP + pp) * GC + c], bi = b_im[(g * NP + pp) * GC + c];
.LBB0_80:
	s_and_b32 s38, s86, 63
	s_lshl_b32 s28, s38, 2
	v_mov_b32_e32 v0, s28
	s_barrier
	v_lshl_or_b32 v208, s38, 10, v6
	v_mov_b32_e32 v209, 0
	v_lshl_add_u64 v[210:211], v[208:209], 2, s[58:59]
	global_load_dword v200, v[210:211], off
	global_load_dword v201, v[210:211], off offset:2048
	v_lshl_add_u64 v[210:211], v[208:209], 2, s[60:61]
	global_load_dword v202, v[210:211], off
	global_load_dword v203, v[210:211], off offset:2048
	v_lshl_add_u64 v[210:211], v[208:209], 2, s[54:55]
	global_load_dword v204, v[210:211], off
	global_load_dword v205, v[210:211], off offset:2048
	v_lshl_add_u64 v[210:211], v[208:209], 2, s[52:53]
	global_load_dword v206, v[210:211], off
	global_load_dword v207, v[210:211], off offset:2048
	global_load_dword v0, v0, s[44:45]
	s_lshl_b32 s87, s38, 6
	v_or_b32_e32 v1, s87, v32
	v_lshlrev_b32_e32 v3, 2, v1
	global_load_dword v2, v3, s[40:41]
	s_nop 0
	global_load_dword v3, v3, s[42:43]
	s_cmp_lt_u32 s86, 64
	s_cselect_b64 s[64:65], -1, 0
	s_waitcnt vmcnt(2)
	v_mul_f32_e32 v4, 0x3fb8aa3b, v0
	v_fma_f32 v5, v0, s51, -v4
	v_rndne_f32_e32 v8, v4
	v_fmac_f32_e32 v5, 0x32a5705f, v0
	v_sub_f32_e32 v4, v4, v8
	v_add_f32_e32 v4, v4, v5
	v_cvt_i32_f32_e32 v13, v8
	v_exp_f32_e32 v4, v4
	v_lshlrev_b32_e32 v8, 3, v1
	v_cmp_ngt_f32_e32 vcc, s56, v0
	v_ldexp_f32 v1, v4, v13
	s_nop 0
	v_cndmask_b32_e32 v1, 0, v1, vcc
	v_cmp_nlt_f32_e32 vcc, s57, v0
	v_lshl_add_u64 v[4:5], s[62:63], 0, v[8:9]
	s_nop 0
	v_cndmask_b32_e32 v0, v56, v1, vcc
	s_waitcnt vmcnt(1)
	v_mul_f32_e32 v13, v2, v0
	s_waitcnt vmcnt(0)
	v_mul_f32_e32 v15, v3, v0
	s_and_saveexec_b64 s[66:67], s[8:9]
	s_cbranch_execz .LBB0_87
	v_mul_f32_e32 v16, v15, v39
	s_waitcnt lgkmcnt(0)
	v_and_b32_e32 v17, 0x7fffffff, v16
	v_cmp_nlt_f32_e64 s[28:29], |v16|, s71
	s_and_saveexec_b64 s[30:31], s[28:29]
	s_xor_b64 s[68:69], exec, s[30:31]
	s_cbranch_execz .LBB0_83
	v_lshrrev_b32_e32 v0, 23, v17
	v_add_u32_e32 v0, 0xffffff88, v0
	v_cmp_lt_u32_e32 vcc, 63, v0
	s_nop 1
	v_cndmask_b32_e32 v1, 0, v60, vcc
	v_add_u32_e32 v0, v1, v0
	v_cmp_lt_u32_e64 s[28:29], 31, v0
	s_nop 1
	v_cndmask_b32_e64 v1, 0, v61, s[28:29]
	v_add_u32_e32 v0, v1, v0
	v_cmp_lt_u32_e64 s[30:31], 31, v0
	s_nop 1
	v_cndmask_b32_e64 v1, 0, v61, s[30:31]
	v_add_u32_e32 v0, v1, v0
	v_and_b32_e32 v1, 0x7fffff, v17
	v_or_b32_e32 v1, 0x800000, v1
	v_mad_u64_u32 v[18:19], s[34:35], v1, s72, 0
	v_mov_b32_e32 v8, v19
	v_mad_u64_u32 v[20:21], s[34:35], v1, s73, v[8:9]
	v_mov_b32_e32 v8, v21
	v_mad_u64_u32 v[22:23], s[34:35], v1, s74, v[8:9]
	v_mov_b32_e32 v8, v23
	v_mad_u64_u32 v[24:25], s[34:35], v1, s75, v[8:9]
	v_mov_b32_e32 v8, v25
	v_mad_u64_u32 v[26:27], s[34:35], v1, s76, v[8:9]
	v_mov_b32_e32 v8, v27
	v_mad_u64_u32 v[28:29], s[34:35], v1, s77, v[8:9]
	v_mov_b32_e32 v8, v29
	v_mad_u64_u32 v[30:31], s[34:35], v1, s78, v[8:9]
	v_cndmask_b32_e32 v19, v28, v24, vcc
	v_cndmask_b32_e32 v1, v30, v26, vcc
	v_cndmask_b32_e32 v21, v31, v28, vcc
	v_cndmask_b32_e64 v8, v1, v19, s[28:29]
	v_cndmask_b32_e64 v1, v21, v1, s[28:29]
	v_cndmask_b32_e32 v21, v26, v22, vcc
	v_cndmask_b32_e64 v19, v19, v21, s[28:29]
	v_cndmask_b32_e64 v1, v1, v8, s[30:31]
	v_cndmask_b32_e64 v8, v8, v19, s[30:31]
	v_sub_u32_e32 v23, 32, v0
	v_alignbit_b32 v25, v1, v8, v23
	v_cmp_eq_u32_e64 s[34:35], 0, v0
	v_cndmask_b32_e32 v18, v22, v18, vcc
	s_nop 0
	v_cndmask_b32_e64 v0, v25, v1, s[34:35]
	v_cndmask_b32_e32 v1, v24, v20, vcc
	v_cndmask_b32_e64 v20, v21, v1, s[28:29]
	v_cndmask_b32_e64 v19, v19, v20, s[30:31]
	v_alignbit_b32 v21, v8, v19, v23
	v_cndmask_b32_e64 v8, v21, v8, s[34:35]
	v_bfe_u32 v25, v0, 29, 1
	v_cndmask_b32_e64 v1, v1, v18, s[28:29]
	v_alignbit_b32 v21, v0, v8, 30
	v_sub_u32_e32 v26, 0, v25
	v_cndmask_b32_e64 v1, v20, v1, s[30:31]
	v_xor_b32_e32 v21, v21, v26
	v_alignbit_b32 v18, v19, v1, v23
	v_cndmask_b32_e64 v18, v18, v19, s[34:35]
	v_ffbh_u32_e32 v19, v21
	v_alignbit_b32 v8, v8, v18, 30
	v_min_u32_e32 v19, 32, v19
	v_alignbit_b32 v1, v18, v1, 30
	v_xor_b32_e32 v8, v8, v26
	v_sub_u32_e32 v20, 31, v19
	v_xor_b32_e32 v1, v1, v26
	v_alignbit_b32 v21, v21, v8, v20
	v_alignbit_b32 v1, v8, v1, v20
	v_alignbit_b32 v8, v21, v1, 9
	v_ffbh_u32_e32 v18, v8
	v_min_u32_e32 v18, 32, v18
	v_lshrrev_b32_e32 v24, 29, v0
	v_not_b32_e32 v20, v18
	v_alignbit_b32 v1, v8, v1, v20
	v_lshlrev_b32_e32 v8, 31, v24
	v_or_b32_e32 v20, 0x33000000, v8
	v_add_lshl_u32 v18, v18, v19, 23
	v_lshrrev_b32_e32 v1, 9, v1
	v_sub_u32_e32 v18, v20, v18
	v_or_b32_e32 v8, 0.5, v8
	v_lshlrev_b32_e32 v19, 23, v19
	v_or_b32_e32 v1, v18, v1
	v_lshrrev_b32_e32 v18, 9, v21
	v_sub_u32_e32 v8, v8, v19
	v_or_b32_e32 v8, v18, v8
	v_mul_f32_e32 v18, 0x3fc90fda, v8
	v_fma_f32 v19, v8, s79, -v18
	v_fmac_f32_e32 v19, 0x33a22168, v8
	v_fmac_f32_e32 v19, 0x3fc90fda, v1
	v_lshrrev_b32_e32 v0, 30, v0
	v_add_f32_e32 v8, v18, v19
	v_add_u32_e32 v18, v25, v0

; DEV void s5_tables(LAS char* shm, char* tab, const float* lam_re, const float* lam_im, const float* log_dt, const float* b_re, const float* b_im,
;                    const float* c_re, const float* c_im) {
;     ...
; #pragma unroll
;             for (int e = 0; e < 2; ++e) { const int o = tid + 512 * e, c = o >> 6, p2 = o & 63;
;                 cc[p2 * 16 + c] = (f32x2){c_re[(g * GC + c) * NP + p2], c_im[(g * GC + c) * NP + p2]}; }
;         }
;         __syncthreads();
;         for (int o = tid; o < 1024; o += 512) {
;             const int pp = o >> 4, c = o & 15; const f32x2 z = crv[pp];
;             const float br = b_re[(g * NP + pp) * GC + c], bi = b_im[(g * NP + pp) * GC + c];
;             bb[pp * 16 + c] = (f32x2){z.x * br - z.y * bi, z.x * bi + z.y * br};
;         }
.LBB0_125:
	s_or_b64 exec, exec, s[66:67]
	v_lshl_or_b32 v0, s38, 10, v32
	v_add_u32_e32 v2, v0, v45
	v_ashrrev_i32_e32 v3, 31, v2
	v_lshlrev_b64 v[2:3], 2, v[2:3]
	v_lshl_add_u64 v[4:5], s[58:59], 0, v[2:3]
	v_lshl_add_u64 v[2:3], s[60:61], 0, v[2:3]
	s_waitcnt vmcnt(0)
	v_mov_b32_e32 v4, v200
	s_nop 0
	v_mov_b32_e32 v5, v202
	v_add_u32_e32 v2, v0, v47
	v_ashrrev_i32_e32 v3, 31, v2
	v_lshlrev_b64 v[2:3], 2, v[2:3]
	s_waitcnt lgkmcnt(0)
	v_lshl_add_u64 v[16:17], s[58:59], 0, v[2:3]
	v_lshl_add_u64 v[2:3], s[60:61], 0, v[2:3]
	v_mov_b32_e32 v16, v201
	s_nop 0
	v_mov_b32_e32 v17, v203
	s_waitcnt vmcnt(2)
	ds_write_b64 v46, v[4:5] offset:25088
	s_waitcnt vmcnt(0)
	ds_write_b64 v48, v[16:17] offset:25088
	s_waitcnt lgkmcnt(0)
	s_barrier
	s_and_saveexec_b64 s[28:29], s[26:27]
	s_cbranch_execz .LBB0_128
	s_mov_b64 s[30:31], 0
	v_mov_b32_e32 v2, v52
	v_mov_b32_e32 v3, v6
.LBB0_127:
	v_ashrrev_i32_e32 v0, 4, v3
	v_add_u32_e32 v1, s87, v0
	v_lshl_or_b32 v4, v1, 4, v38
	v_ashrrev_i32_e32 v5, 31, v4
	v_lshlrev_b64 v[4:5], 2, v[4:5]
	v_lshl_add_u64 v[16:17], s[52:53], 0, v[4:5]
	v_lshl_add_u64 v[4:5], s[54:55], 0, v[4:5]
	v_mov_b32_e32 v4, v204
	s_nop 0
	v_mov_b32_e32 v8, v206
	v_lshl_add_u32 v0, v0, 3, 0
	ds_read_b64 v[16:17], v0 offset:33280
	v_add_u32_e32 v1, 0x200, v3
	v_cmp_lt_i32_e32 vcc, s84, v3
	s_or_b64 s[30:31], vcc, s[30:31]
	v_mov_b32_e32 v3, v1
	s_waitcnt vmcnt(1) lgkmcnt(0)
	v_pk_mul_f32 v[4:5], v[16:17], v[4:5] op_sel:[1,0] op_sel_hi:[0,0]
	s_waitcnt vmcnt(0)
	v_pk_fma_f32 v[18:19], v[16:17], v[8:9], v[4:5] neg_lo:[0,0,1] neg_hi:[0,0,1]
	v_pk_fma_f32 v[4:5], v[16:17], v[8:9], v[4:5] op_sel_hi:[1,0,1]
	s_nop 0
	v_mov_b32_e32 v19, v5
	ds_write_b64 v2, v[18:19]
	v_add_u32_e32 v2, 0x1000, v2
	v_mov_b32_e32 v204, v205
	v_mov_b32_e32 v206, v207
	s_andn2_b64 exec, exec, s[30:31]
	s_cbranch_execnz .LBB0_127

; DEV void s5_tables(LAS char* shm, char* tab, const float* lam_re, const float* lam_im, const float* log_dt, const float* b_re, const float* b_im,
;                    const float* c_re, const float* c_im) {
;     ...
;             const int pp = tid & 63, eg = tid >> 6;
;             const float lr = lam_re[g * NP + pp], li = lam_im[g * NP + pp], dt = expf(log_dt[g]);
;             const float xr = lr * dt, xi = li * dt;
; #pragma unroll
;             for (int k = 0; k < 5; ++k) {
;                 const int e = eg + 8 * k;
;                 if (e <= 32) {
;                     const float m_ = expf((float)e * xr); float sn, cs; sincosf((float)e * xi, &sn, &cs);
;     ...
;             for (int e = 0; e < 2; ++e) { const int o = tid + 512 * e, c = o >> 6, p2 = o & 63;
;                 cc[p2 * 16 + c] = (f32x2){c_re[(g * GC + c) * NP + p2], c_im[(g * GC + c) * NP + p2]}; }
;         }
;         __syncthreads();
;         for (int o = tid; o < 1024; o += 512) {
;             const int pp = o >> 4, c = o & 15; const f32x2 z = crv[pp];
;             const float br = b_re[(g * NP + pp) * GC + c], bi = b_im[(g * NP + pp) * GC + c];
.LBB0_935:
	s_and_b32 s40, s2, 63
	s_lshl_b32 s54, s40, 6
	v_or_b32_e32 v0, s54, v28
	v_lshlrev_b32_e32 v1, 2, v0
	s_lshl_b32 s0, s40, 2
	s_barrier
	v_lshl_or_b32 v208, s40, 10, v6
	v_mov_b32_e32 v209, 0
	v_lshl_add_u64 v[210:211], v[208:209], 2, s[88:89]
	global_load_dword v200, v[210:211], off
	global_load_dword v201, v[210:211], off offset:2048
	v_lshl_add_u64 v[210:211], v[208:209], 2, s[90:91]
	global_load_dword v202, v[210:211], off
	global_load_dword v203, v[210:211], off offset:2048
	v_lshl_add_u64 v[210:211], v[208:209], 2, s[86:87]
	global_load_dword v204, v[210:211], off
	global_load_dword v205, v[210:211], off offset:2048
	v_lshl_add_u64 v[210:211], v[208:209], 2, s[84:85]
	global_load_dword v206, v[210:211], off
	global_load_dword v207, v[210:211], off offset:2048
	global_load_dword v2, v1, s[46:47]
	global_load_dword v3, v1, s[82:83]
	v_mov_b32_e32 v1, s0
	global_load_dword v1, v1, s[42:43] offset:256
	s_cmp_lt_u32 s2, 64
	s_cselect_b64 s[94:95], -1, 0
	s_waitcnt vmcnt(0)
	v_mul_f32_e32 v4, 0x3fb8aa3b, v1
	v_fma_f32 v5, v1, s65, -v4
	v_rndne_f32_e32 v8, v4
	v_fmac_f32_e32 v5, 0x32a5705f, v1
	v_sub_f32_e32 v4, v4, v8
	v_add_f32_e32 v4, v4, v5
	v_exp_f32_e32 v4, v4
	v_cvt_i32_f32_e32 v5, v8
	v_cmp_ngt_f32_e32 vcc, s67, v1
	v_lshlrev_b32_e32 v8, 3, v0
	v_ldexp_f32 v4, v4, v5
	v_cndmask_b32_e32 v4, 0, v4, vcc
	v_cmp_nlt_f32_e32 vcc, s68, v1
	s_nop 1
	v_cndmask_b32_e32 v1, v52, v4, vcc
	v_mul_f32_e32 v13, v2, v1
	v_mul_f32_e32 v15, v3, v1
	v_lshl_add_u64 v[4:5], s[92:93], 0, v[8:9]
	s_and_saveexec_b64 s[96:97], s[12:13]
	s_cbranch_execz .LBB0_942
	v_mul_f32_e32 v16, v15, v35
	v_and_b32_e32 v17, 0x7fffffff, v16
	v_cmp_nlt_f32_e64 s[0:1], |v16|, s69
	s_and_saveexec_b64 s[30:31], s[0:1]
	s_xor_b64 s[0:1], exec, s[30:31]
	s_cbranch_execz .LBB0_938
	v_lshrrev_b32_e32 v0, 23, v17
	v_add_u32_e32 v0, 0xffffff88, v0
	v_cmp_lt_u32_e32 vcc, 63, v0
	s_nop 1
	v_cndmask_b32_e32 v1, 0, v56, vcc
	v_add_u32_e32 v0, v1, v0
	v_cmp_lt_u32_e64 s[30:31], 31, v0
	s_nop 1
	v_cndmask_b32_e64 v1, 0, v57, s[30:31]
	v_add_u32_e32 v0, v1, v0
	v_cmp_lt_u32_e64 s[34:35], 31, v0
	s_nop 1
	v_cndmask_b32_e64 v1, 0, v57, s[34:35]
	v_add_u32_e32 v62, v1, v0
	v_and_b32_e32 v0, 0x7fffff, v17
	v_or_b32_e32 v60, 0x800000, v0
	v_mad_u64_u32 v[0:1], s[36:37], v60, s71, 0
	v_mov_b32_e32 v8, v1
	v_mad_u64_u32 v[18:19], s[36:37], v60, s72, v[8:9]
	v_mov_b32_e32 v8, v19
	v_mad_u64_u32 v[20:21], s[36:37], v60, s73, v[8:9]
	v_mov_b32_e32 v8, v21
	v_mad_u64_u32 v[22:23], s[36:37], v60, s74, v[8:9]
	v_mov_b32_e32 v8, v23
	v_mad_u64_u32 v[24:25], s[36:37], v60, s75, v[8:9]
	v_mov_b32_e32 v8, v25
	v_mad_u64_u32 v[26:27], s[36:37], v60, s76, v[8:9]
	v_mov_b32_e32 v8, v27
	v_mad_u64_u32 v[60:61], s[36:37], v60, s77, v[8:9]
	v_cndmask_b32_e32 v1, v26, v22, vcc
	v_cndmask_b32_e32 v8, v60, v24, vcc
	v_cndmask_b32_e32 v21, v61, v26, vcc
	v_cndmask_b32_e64 v19, v8, v1, s[30:31]
	v_cndmask_b32_e64 v8, v21, v8, s[30:31]
	v_cndmask_b32_e32 v21, v24, v20, vcc
	v_cndmask_b32_e64 v1, v1, v21, s[30:31]
	v_cndmask_b32_e64 v8, v8, v19, s[34:35]
	v_cndmask_b32_e64 v19, v19, v1, s[34:35]
	v_sub_u32_e32 v23, 32, v62
	v_alignbit_b32 v24, v8, v19, v23
	v_cmp_eq_u32_e64 s[36:37], 0, v62
	v_cndmask_b32_e32 v0, v20, v0, vcc
	s_nop 0
	v_cndmask_b32_e64 v24, v24, v8, s[36:37]
	v_cndmask_b32_e32 v8, v22, v18, vcc
	v_cndmask_b32_e64 v18, v21, v8, s[30:31]
	v_cndmask_b32_e64 v1, v1, v18, s[34:35]
	v_alignbit_b32 v21, v19, v1, v23
	v_cndmask_b32_e64 v19, v21, v19, s[36:37]
	v_bfe_u32 v25, v24, 29, 1
	v_cndmask_b32_e64 v0, v8, v0, s[30:31]
	v_alignbit_b32 v21, v24, v19, 30
	v_sub_u32_e32 v26, 0, v25
	v_cndmask_b32_e64 v0, v18, v0, s[34:35]
	v_xor_b32_e32 v21, v21, v26
	v_alignbit_b32 v8, v1, v0, v23
	v_cndmask_b32_e64 v1, v8, v1, s[36:37]
	v_ffbh_u32_e32 v18, v21
	v_alignbit_b32 v8, v19, v1, 30
	v_min_u32_e32 v18, 32, v18
	v_alignbit_b32 v0, v1, v0, 30
	v_xor_b32_e32 v8, v8, v26
	v_sub_u32_e32 v19, 31, v18
	v_xor_b32_e32 v0, v0, v26
	v_alignbit_b32 v20, v21, v8, v19
	v_alignbit_b32 v0, v8, v0, v19
	v_alignbit_b32 v1, v20, v0, 9
	v_ffbh_u32_e32 v8, v1
	v_min_u32_e32 v8, 32, v8
	v_lshrrev_b32_e32 v22, 29, v24
	v_not_b32_e32 v19, v8
	v_alignbit_b32 v0, v1, v0, v19
	v_lshlrev_b32_e32 v1, 31, v22
	v_or_b32_e32 v19, 0x33000000, v1
	v_add_lshl_u32 v8, v8, v18, 23
	v_lshrrev_b32_e32 v0, 9, v0
	v_sub_u32_e32 v8, v19, v8
	v_or_b32_e32 v1, 0.5, v1
	v_lshlrev_b32_e32 v18, 23, v18
	v_or_b32_e32 v0, v8, v0
	v_lshrrev_b32_e32 v8, 9, v20
	v_sub_u32_e32 v1, v1, v18
	v_or_b32_e32 v1, v8, v1
	v_mul_f32_e32 v8, 0x3fc90fda, v1
	v_fma_f32 v18, v1, s80, -v8
	v_fmac_f32_e32 v18, 0x33a22168, v1
	v_fmac_f32_e32 v18, 0x3fc90fda, v0
	v_lshrrev_b32_e32 v0, 30, v24
	v_add_f32_e32 v8, v8, v18
	v_add_u32_e32 v18, v25, v0

; DEV void s5_tables(LAS char* shm, char* tab, const float* lam_re, const float* lam_im, const float* log_dt, const float* b_re, const float* b_im,
;                    const float* c_re, const float* c_im) {
;     ...
; #pragma unroll
;             for (int e = 0; e < 2; ++e) { const int o = tid + 512 * e, c = o >> 6, p2 = o & 63;
;                 cc[p2 * 16 + c] = (f32x2){c_re[(g * GC + c) * NP + p2], c_im[(g * GC + c) * NP + p2]}; }
;         }
;         __syncthreads();
;         for (int o = tid; o < 1024; o += 512) {
;             const int pp = o >> 4, c = o & 15; const f32x2 z = crv[pp];
;             const float br = b_re[(g * NP + pp) * GC + c], bi = b_im[(g * NP + pp) * GC + c];
;             bb[pp * 16 + c] = (f32x2){z.x * br - z.y * bi, z.x * bi + z.y * br};
;         }
.LBB0_980:
	s_or_b64 exec, exec, s[96:97]
	v_lshl_or_b32 v4, s40, 10, v28
	v_add_u32_e32 v0, v4, v41
	v_ashrrev_i32_e32 v1, 31, v0
	v_lshlrev_b64 v[0:1], 2, v[0:1]
	v_lshl_add_u64 v[2:3], s[88:89], 0, v[0:1]
	v_lshl_add_u64 v[0:1], s[90:91], 0, v[0:1]
	s_waitcnt vmcnt(0)
	v_mov_b32_e32 v2, v200
	s_nop 0
	v_mov_b32_e32 v3, v202
	v_add_u32_e32 v0, v4, v43
	v_ashrrev_i32_e32 v1, 31, v0
	v_lshlrev_b64 v[0:1], 2, v[0:1]
	s_waitcnt vmcnt(0)
	ds_write_b64 v42, v[2:3] offset:25088
	v_lshl_add_u64 v[2:3], s[88:89], 0, v[0:1]
	v_lshl_add_u64 v[0:1], s[90:91], 0, v[0:1]
	v_mov_b32_e32 v2, v201
	s_nop 0
	v_mov_b32_e32 v3, v203
	s_waitcnt vmcnt(0)
	ds_write_b64 v44, v[2:3] offset:25088
	s_waitcnt lgkmcnt(0)
	s_barrier
	s_and_saveexec_b64 s[0:1], s[6:7]
	s_cbranch_execz .LBB0_983
	s_mov_b64 s[30:31], 0
	v_mov_b32_e32 v2, v48
	v_mov_b32_e32 v3, v6
.LBB0_982:
	v_ashrrev_i32_e32 v8, 4, v3
	v_add_u32_e32 v0, s54, v8
	v_lshl_or_b32 v0, v0, 4, v34
	v_ashrrev_i32_e32 v1, 31, v0
	v_lshlrev_b64 v[0:1], 2, v[0:1]
	v_lshl_add_u64 v[4:5], s[84:85], 0, v[0:1]
	v_lshl_add_u64 v[0:1], s[86:87], 0, v[0:1]
	v_mov_b32_e32 v0, v204
	s_nop 0
	v_mov_b32_e32 v4, v206
	s_movk_i32 s34, 0x1ff
	v_add_u32_e32 v1, 0x200, v3
	v_cmp_lt_i32_e32 vcc, s34, v3
	v_lshl_add_u32 v3, v8, 3, 0
	ds_read_b64 v[16:17], v3 offset:33280
	v_mov_b32_e32 v3, v1
	s_or_b64 s[30:31], vcc, s[30:31]
	s_waitcnt vmcnt(1) lgkmcnt(0)
	v_pk_mul_f32 v[0:1], v[16:17], v[0:1] op_sel:[1,0] op_sel_hi:[0,0]
	s_waitcnt vmcnt(0)
	v_pk_fma_f32 v[18:19], v[16:17], v[4:5], v[0:1] neg_lo:[0,0,1] neg_hi:[0,0,1]
	v_pk_fma_f32 v[0:1], v[16:17], v[4:5], v[0:1] op_sel_hi:[1,0,1]
	s_nop 0
	v_mov_b32_e32 v19, v1
	ds_write_b64 v2, v[18:19]
	v_add_u32_e32 v2, 0x1000, v2
	v_mov_b32_e32 v204, v205
	v_mov_b32_e32 v206, v207
	s_andn2_b64 exec, exec, s[30:31]
	s_cbranch_execnz .LBB0_982
